# merge GEMM main-loop head moved to byte phase 40, other GEMM loop heads pinned to their previous phases (placement trial)
# speedup vs baseline: 1.0035x; 1.0035x over previous
;     __device__ __forceinline__ bool next(int i, Unit& u) const { return static_next((long)i * G + c, nM, nN, u); }
;     __device__ __forceinline__ const char* aptr(const Unit& u) const { return (const char*)(A + (size_t)u.pm * 256 * K); }
;     __device__ __forceinline__ const char* bptr(const Unit& u) const { return (const char*)(B + (size_t)u.pn * 256 * K); }
;     __device__ __forceinline__ bool next(int i, Unit& u) const { if (i > 0 || c >= 32) return false; u.z = c >> 4; u.pm = c & 15; u.pn = 0; return true; }
;     __device__ __forceinline__ const char* aptr(const Unit& u) const { return (const char*)(A0 + ((size_t)u.z * 4096 + (size_t)u.pm * 256) * 2048); }
;     __device__ __forceinline__ const char* bptr(const Unit& u) const { return (const char*)(W1T + (size_t)u.z * 256 * 2048); }
;     __device__ __forceinline__ bool next(int i, Unit& u) const { if (i > 1) return false; const int x = c & 7, k = c >> 3; u.pm = 32 * i + 4 * x + (k >> 3); u.pn = k & 7; u.z = 0; return true; }
;     __device__ __forceinline__ const char* aptr(const Unit& u) const { return (const char*)(A + (size_t)u.pm * 256 * DM); }
;     __device__ __forceinline__ const char* bptr(const Unit& u) const { return (const char*)(B + (size_t)u.pn * 256 * DM); }
;     __device__ __forceinline__ bool next(int i, Unit& u) const { const bool ok = static_next((long)(i >> 2) * G + c, 64, 8, u); u.z = i & 3; return ok; }
;     __device__ __forceinline__ const char* aptr(const Unit& u) const { return (const char*)(O + ((size_t)u.z * MT + (size_t)u.pm * 256) * DBR); }
;     __device__ __forceinline__ const char* bptr(const Unit& u) const { return (const char*)(WBR + ((size_t)u.z * DM + (size_t)u.pn * 256) * DBR); }
; template <class Epi, class Sched>
; __device__ __forceinline__ void gemm_phase(LAS unsigned char* lds, const int K, const Sched& S, const Epi& E) {
;     ...
;         const bool has_next = S.next(ui + 1, nxt);
;         const char* nA = has_next ? S.aptr(nxt) : cA; const char* nB = has_next ? S.bptr(nxt) : cB;
;         for (int t = 0; t < nt; t += 2) {
;             const bool last = (t == nt - 2);
;             const char* a1 = cA + (size_t)(t + 1) * kstep;
;             const char* a2 = last ? nA : cA + (size_t)(t + 2) * kstep; const char* b2 = last ? nB : cB + (size_t)(t + 2) * kstep;
;             const char* a3 = a2 + kstep; const char* b3 = b2 + kstep;
.LBB0_137:
	s_and_b32 s76, s71, 3
	s_ashr_i32 s17, s16, 31
	s_lshl_b32 s15, s76, 25
	s_lshl_b64 s[18:19], s[16:17], 19
	s_add_u32 s15, s28, s15
	s_addc_u32 s17, s29, 0
	s_add_u32 s18, s15, s18
	s_addc_u32 s19, s17, s19
	s_and_b64 s[20:21], s[6:7], exec
	s_cselect_b32 s17, s19, s9
	s_cselect_b32 s86, s18, s8
	s_ashr_i32 s15, s14, 31
	s_lshl_b32 s26, s76, 22
	s_lshl_b64 s[20:21], s[14:15], 19
	s_add_u32 s15, s30, s26
	s_addc_u32 s26, s31, 0
	s_add_u32 s20, s15, s20
	s_addc_u32 s21, s26, s21
	s_and_b64 s[26:27], s[6:7], exec
	s_cselect_b32 s15, s21, s25
	s_cselect_b32 s87, s20, s24
	s_add_u32 s8, s8, 0x40080
	s_addc_u32 s9, s9, 0
	s_add_u32 s94, s24, 0x100
	v_mov_b32_e32 v2, 0
	s_addc_u32 s95, s25, 0
	s_mov_b32 vcc_lo, -2
	v_mov_b32_e32 v3, v2
	v_mov_b32_e32 v4, v2
	v_mov_b32_e32 v5, v2
	v_mov_b32_e32 v6, v2
	v_mov_b32_e32 v7, v2
	v_mov_b32_e32 v8, v2
	v_mov_b32_e32 v9, v2
	v_mov_b32_e32 v18, v2
	v_mov_b32_e32 v19, v2
	v_mov_b32_e32 v20, v2
	v_mov_b32_e32 v21, v2
	v_mov_b32_e32 v22, v2
	v_mov_b32_e32 v23, v2
	v_mov_b32_e32 v24, v2
	v_mov_b32_e32 v25, v2
	v_mov_b32_e32 v34, v2
	v_mov_b32_e32 v35, v2
	v_mov_b32_e32 v36, v2
	v_mov_b32_e32 v37, v2
	v_mov_b32_e32 v38, v2
	v_mov_b32_e32 v39, v2
	v_mov_b32_e32 v40, v2
	v_mov_b32_e32 v41, v2
	v_mov_b32_e32 v50, v2
	v_mov_b32_e32 v51, v2
	v_mov_b32_e32 v52, v2
	v_mov_b32_e32 v53, v2
	v_mov_b32_e32 v54, v2
	v_mov_b32_e32 v55, v2
	v_mov_b32_e32 v56, v2
	v_mov_b32_e32 v57, v2
	v_mov_b32_e32 v10, v2
	v_mov_b32_e32 v11, v2
	v_mov_b32_e32 v12, v2
	v_mov_b32_e32 v13, v2
	v_mov_b32_e32 v14, v2
	v_mov_b32_e32 v15, v2
	v_mov_b32_e32 v16, v2
	v_mov_b32_e32 v17, v2
	v_mov_b32_e32 v26, v2
	v_mov_b32_e32 v27, v2
	v_mov_b32_e32 v28, v2
	v_mov_b32_e32 v29, v2
	v_mov_b32_e32 v30, v2
	v_mov_b32_e32 v31, v2
	v_mov_b32_e32 v32, v2
	v_mov_b32_e32 v33, v2
	v_mov_b32_e32 v42, v2
	v_mov_b32_e32 v43, v2
	v_mov_b32_e32 v44, v2
	v_mov_b32_e32 v45, v2
	v_mov_b32_e32 v46, v2
	v_mov_b32_e32 v47, v2
	v_mov_b32_e32 v48, v2
	v_mov_b32_e32 v49, v2
	v_mov_b32_e32 v58, v2
	v_mov_b32_e32 v59, v2
	v_mov_b32_e32 v60, v2
	v_mov_b32_e32 v61, v2
	v_mov_b32_e32 v62, v2
	v_mov_b32_e32 v63, v2
	v_mov_b32_e32 v64, v2
	v_mov_b32_e32 v65, v2
	v_mov_b32_e32 v66, v2
	v_mov_b32_e32 v67, v2
	v_mov_b32_e32 v68, v2
	v_mov_b32_e32 v69, v2
	v_mov_b32_e32 v70, v2
	v_mov_b32_e32 v71, v2
	v_mov_b32_e32 v72, v2
	v_mov_b32_e32 v73, v2
	v_mov_b32_e32 v82, v2
	v_mov_b32_e32 v83, v2
	v_mov_b32_e32 v84, v2
	v_mov_b32_e32 v85, v2
	v_mov_b32_e32 v86, v2
	v_mov_b32_e32 v87, v2
	v_mov_b32_e32 v88, v2
	v_mov_b32_e32 v89, v2
	v_mov_b32_e32 v98, v2
	v_mov_b32_e32 v99, v2
	v_mov_b32_e32 v100, v2
	v_mov_b32_e32 v101, v2
	v_mov_b32_e32 v102, v2
	v_mov_b32_e32 v103, v2
	v_mov_b32_e32 v104, v2
	v_mov_b32_e32 v105, v2
	v_mov_b32_e32 v114, v2
	v_mov_b32_e32 v115, v2
	v_mov_b32_e32 v116, v2
	v_mov_b32_e32 v117, v2
	v_mov_b32_e32 v118, v2
	v_mov_b32_e32 v119, v2
	v_mov_b32_e32 v120, v2
	v_mov_b32_e32 v121, v2
	v_mov_b32_e32 v74, v2
	v_mov_b32_e32 v75, v2
	v_mov_b32_e32 v76, v2
	v_mov_b32_e32 v77, v2
	v_mov_b32_e32 v78, v2
	v_mov_b32_e32 v79, v2
	v_mov_b32_e32 v80, v2
	v_mov_b32_e32 v81, v2
	v_mov_b32_e32 v90, v2
	v_mov_b32_e32 v91, v2
	v_mov_b32_e32 v92, v2
	v_mov_b32_e32 v93, v2
	v_mov_b32_e32 v94, v2
	v_mov_b32_e32 v95, v2
	v_mov_b32_e32 v96, v2
	v_mov_b32_e32 v97, v2
	v_mov_b32_e32 v106, v2
	v_mov_b32_e32 v107, v2
	v_mov_b32_e32 v108, v2
	v_mov_b32_e32 v109, v2
	v_mov_b32_e32 v110, v2
	v_mov_b32_e32 v111, v2
	v_mov_b32_e32 v112, v2
	v_mov_b32_e32 v113, v2
	v_mov_b32_e32 v122, v2
	v_mov_b32_e32 v123, v2
	v_mov_b32_e32 v124, v2
	v_mov_b32_e32 v125, v2
	v_mov_b32_e32 v126, v2
	v_mov_b32_e32 v127, v2
	v_mov_b32_e32 v128, v2
	v_mov_b32_e32 v129, v2
	.p2align	6
	s_nop 0
	s_nop 0
	s_nop 0
	s_nop 0
	s_nop 0
	s_nop 0
	s_nop 0
	s_nop 0
	s_nop 0
	s_nop 0
